# grid barrier: cache invalidate issued once at arrival (overlaps the arrival atomic), no invalidate after the leader's write-back
# speedup vs baseline: 1.0030x; 1.0030x over previous
.LBB0_1095:
	v_readlane_b32 s8, v252, 22
	v_readlane_b32 s9, v252, 23
	s_and_b64 vcc, exec, s[8:9]
	s_cbranch_vccz .LBB0_1149
	s_waitcnt vmcnt(0)
	s_waitcnt vmcnt(0)
	s_barrier
	s_mov_b64 s[2:3], exec
	v_readlane_b32 s8, v251, 2
	v_readlane_b32 s9, v251, 3
	s_and_b64 s[8:9], s[2:3], s[8:9]
	s_mov_b64 exec, s[8:9]
	s_cbranch_execz .LBB0_1148
	v_readlane_b32 s8, v254, 12
	s_waitcnt vmcnt(0) expcnt(0) lgkmcnt(0)
	buffer_inv sc1
	s_nop 0
	v_mov_b32_e32 v0, s8
	ds_read_b32 v3, v0
	v_readlane_b32 s8, v254, 13
	s_waitcnt lgkmcnt(0)
	v_cmp_ne_u32_e32 vcc, 0, v3
	v_mov_b32_e32 v0, s8
	ds_read_b32 v2, v0
	s_cbranch_vccnz .LBB0_1112
	s_mov_b32 s14, 1
	s_branch .LBB0_1100

.LBB0_1114:
	s_or_b64 exec, exec, s[8:9]
	v_cvt_f32_u32_e32 v5, v3
	s_waitcnt vmcnt(0)
	v_readfirstlane_b32 s8, v4
	v_sub_u32_e32 v4, 0, v3
	v_rcp_iflag_f32_e32 v5, v5
	v_add_u32_e32 v6, s8, v0
	v_mul_f32_e32 v5, 0x4f7ffffe, v5
	v_cvt_u32_f32_e32 v5, v5
	v_mul_lo_u32 v0, v4, v5
	v_mul_hi_u32 v0, v5, v0
	v_add_u32_e32 v0, v5, v0
	v_mul_hi_u32 v0, v6, v0
	v_mul_lo_u32 v4, v0, v3
	v_sub_u32_e32 v4, v6, v4
	v_add_u32_e32 v5, 1, v0
	v_cmp_ge_u32_e32 vcc, v4, v3
	s_nop 1
	v_cndmask_b32_e32 v0, v0, v5, vcc
	v_sub_u32_e32 v5, v4, v3
	v_cndmask_b32_e32 v4, v4, v5, vcc
	v_add_u32_e32 v5, 1, v0
	v_cmp_ge_u32_e32 vcc, v4, v3
	v_add_u32_e32 v4, 1, v6
	s_nop 0
	v_cndmask_b32_e32 v0, v0, v5, vcc
	v_add_u32_e32 v7, 1, v0
	v_mul_lo_u32 v5, v3, v0
	v_add_u32_e32 v3, v5, v3
	v_cmp_ne_u32_e32 vcc, v4, v3
	s_and_saveexec_b64 s[8:9], vcc
	s_xor_b64 s[8:9], exec, s[8:9]
	s_cbranch_execz .LBB0_1128
	v_readlane_b32 s10, v253, 28
	v_readlane_b32 s11, v253, 29
	s_waitcnt lgkmcnt(0)
	s_nop 3
	global_load_dword v2, v1, s[10:11] sc1
	s_waitcnt vmcnt(0)
	v_cmp_eq_u32_e32 vcc, v2, v0
	s_and_saveexec_b64 s[10:11], vcc
	s_cbranch_execz .LBB0_1127
	s_mov_b32 s24, 1
	s_mov_b64 s[12:13], 0
	s_branch .LBB0_1118

.LBB0_1128:
	s_andn2_saveexec_b64 s[8:9], s[8:9]
	s_cbranch_execz .LBB0_1148
	s_mov_b64 s[8:9], exec
	buffer_wbl2 sc1
	s_waitcnt lgkmcnt(0)
	s_waitcnt vmcnt(0)
	v_readfirstlane_b32 s22, v7
	v_readfirstlane_b32 s28, v2
	v_readlane_b32 s10, v253, 30
	v_readlane_b32 s11, v253, 31
	v_readlane_b32 s20, v253, 26
	s_sub_u32 s21, s20, s10
	s_add_u32 s21, s21, 0x2000
	s_lshr_b32 s21, s21, 6
	s_add_u32 s10, s10, 0x8000
	s_addc_u32 s11, s11, 0
	v_mov_b32_e32 v4, s22
	v_mov_b32_e32 v5, s21
	s_nop 1
	global_store_dword v5, v4, s[10:11] sc1
	s_mov_b64 s[26:27], exec
	s_mov_b64 exec, 0xff
	v_mbcnt_lo_u32_b32 v6, -1, 0
	v_lshlrev_b32_e32 v6, 2, v6
